# v086 + tile 0 enters through its own out-of-line top (no per-tile tile-0 test), near-flag move placed behind the first QK MFMA
# speedup vs baseline: 1.0010x; 1.0010x over previous
; #define ALAS __attribute__((address_space(3)))
; template <int N> __device__ __forceinline__ void wait_bar() { asm volatile("s_waitcnt vmcnt(%0) lgkmcnt(0)\n\ts_barrier" :: "n"(N) : "memory"); }
; template <bool WIN> ...
;     ...
;     for (int tr = 0; tr < NT; ++tr) {
;         if (tr + 2 < NT) wait_bar<2 * NPW>(); else if (tr + 1 < NT) wait_bar<NPW>(); else wait_bar<0>();
;         if (tr + 3 < NT) AT_DMA(tr + 3);
;         const int k0 = (t_lo + tr) * 64;
;         const bool skip = WIN && (k0 > qw + 31 + 128 || k0 + 63 < qw - 128);
;         if (!skip) {
;             const bool near = WIN || ((k0 - (qw + 31)) < 128 && (qw - (k0 + 63)) < 128);
;             const float cinit = near ? 0.f : (k0 > qw ? cfar_hi : cfar_lo);
;             if (__builtin_expect(cinit != cbase, 0)) { cbase = cinit; asm volatile("" ::: "memory");
; #pragma unroll
;                 for (int r = 0; r < 16; ++r) cvec[r] = cbase - m_ref; }
;             f32x16 s0, s1;
;             const ALAS unsigned char* sb = lds + (tr & (NSTG - 1)) * STAGE;
;             {
;                 bf16x8 ka[8];
; #pragma unroll
;                 for (int ds = 0; ds < 4; ++ds) { ka[2 * ds] = *(const ALAS bf16x8*)(sb + kx[ds]); ka[2 * ds + 1] = *(const ALAS bf16x8*)(sb + kx[ds] + 4096); }
;                 __builtin_amdgcn_sched_barrier(0);
;                 s0 = __builtin_amdgcn_mfma_f32_32x32x16_bf16(ka[0], qf(0), cvec, 0, 0, 0);
;                 s1 = __builtin_amdgcn_mfma_f32_32x32x16_bf16(ka[1], qf(0), cvec, 0, 0, 0);
; #pragma unroll
;                 for (int ds = 1; ds < 4; ++ds) {
;                     s0 = __builtin_amdgcn_mfma_f32_32x32x16_bf16(ka[2 * ds], qf(ds), s0, 0, 0, 0);
;                     s1 = __builtin_amdgcn_mfma_f32_32x32x16_bf16(ka[2 * ds + 1], qf(ds), s1, 0, 0, 0);
;                 }
;             }
;             bf16x8 va[2 * NDB], vc[2 * NDB];
; #pragma unroll
;             for (int kk = 0; kk < 2; ++kk)
; #pragma unroll
;                 for (int db = 0; db < NDB; ++db) va[kk * NDB + db] = *(const ALAS bf16x8*)(sb + vx[kk] + db * 4096);
.LSPp_top:
	s_cmpk_gt_u32 s86, 124
	s_cbranch_scc1 .LSPp_slowtop
	s_waitcnt vmcnt(4) lgkmcnt(0)
	s_barrier
	s_cmp_eq_u32 m0, s100
	s_cbranch_scc0 .LSPp_cin
.LSPp_qk:
	s_mov_b32 m0, s98
	v_mfma_f32_32x32x16_bf16 v[98:113], v[130:133], v[126:129], v[66:81]
	s_mov_b32 s64, s65
	global_load_lds_dwordx4 v[174:175], off
	s_add_i32 m0, s98, 0x2000
	v_mfma_f32_32x32x16_bf16 v[82:97], v[134:137], v[126:129], v[66:81]
	global_load_lds_dwordx4 v[208:209], off
	s_add_i32 m0, s101, 0x4000
	v_mfma_f32_32x32x16_bf16 v[98:113], v[138:141], v[122:125], v[98:113]
	global_load_lds_dwordx4 v[172:173], off
	s_add_i32 m0, s101, 0x6000
	v_mfma_f32_32x32x16_bf16 v[82:97], v[142:145], v[122:125], v[82:97]
	global_load_lds_dwordx4 v[210:211], off
	v_add3_u32 v236, s99, v179, v187
	ds_read_b128 v[130:133], v236 offset:16384
	ds_read_b128 v[134:137], v236 offset:20480
	ds_read_b128 v[138:141], v236 offset:24576
	ds_read_b128 v[142:145], v236 offset:28672
	v_mfma_f32_32x32x16_bf16 v[98:113], v[146:149], v[118:121], v[98:113]
	v_mfma_f32_32x32x16_bf16 v[82:97], v[150:153], v[118:121], v[82:97]
	v_mfma_f32_32x32x16_bf16 v[98:113], v[158:161], v[114:117], v[98:113]
	v_mfma_f32_32x32x16_bf16 v[82:97], v[204:207], v[114:117], v[82:97]
	v_add3_u32 v237, s99, v181, v187
	ds_read_b128 v[146:149], v237 offset:16384
	ds_read_b128 v[150:153], v237 offset:20480
	ds_read_b128 v[154:157], v237 offset:24576
	ds_read_b128 v[158:161], v237 offset:28672
	s_nop 0
	s_branch .LSPp_vrd2

; #define ALAS __attribute__((address_space(3)))
; template <int N> __device__ __forceinline__ void wait_bar() { asm volatile("s_waitcnt vmcnt(%0) lgkmcnt(0)\n\ts_barrier" :: "n"(N) : "memory"); }
; #define AT_DMA(tr) do { const unsigned sb_ = (unsigned)__builtin_amdgcn_readfirstlane(dk + (((tr) & (NSTG - 1)) * STAGE)); const size_t ko_ = (size_t)(tr) * 26 * 4096, vo_ = (size_t)(tr) * 640 * 64; \
;         glds16(kg + ko_, sb_ + OFF_K0); if (!WIN) glds16(kg + ko_ + 4096, sb_ + OFF_K1); glds16(vg + vo_, sb_ + OFF_V); if (!WIN) glds16(vg + vo_ + 64 * 64, sb_ + OFF_V + 8192); } while (0)
; template <bool WIN> ...
;     ...
;         if (tr + 2 < NT) wait_bar<2 * NPW>(); else if (tr + 1 < NT) wait_bar<NPW>(); else wait_bar<0>();
;         if (tr + 3 < NT) AT_DMA(tr + 3);
;         const int k0 = (t_lo + tr) * 64;
;         const bool skip = WIN && (k0 > qw + 31 + 128 || k0 + 63 < qw - 128);
;         if (!skip) {
;             const bool near = WIN || ((k0 - (qw + 31)) < 128 && (qw - (k0 + 63)) < 128);
;             const float cinit = near ? 0.f : (k0 > qw ? cfar_hi : cfar_lo);
;             if (__builtin_expect(cinit != cbase, 0)) { cbase = cinit; asm volatile("" ::: "memory");
; #pragma unroll
;                 for (int r = 0; r < 16; ++r) cvec[r] = cbase - m_ref; }
;             f32x16 s0, s1;
;             const ALAS unsigned char* sb = lds + (tr & (NSTG - 1)) * STAGE;
;             {
;                 bf16x8 ka[8];
; #pragma unroll
;                 for (int ds = 0; ds < 4; ++ds) { ka[2 * ds] = *(const ALAS bf16x8*)(sb + kx[ds]); ka[2 * ds + 1] = *(const ALAS bf16x8*)(sb + kx[ds] + 4096); }
.LSPp_top0:
	s_waitcnt vmcnt(4) lgkmcnt(0)
	s_barrier
	ds_read_b128 v[130:133], v212
	ds_read_b128 v[134:137], v212 offset:4096
	ds_read_b128 v[138:141], v213
	ds_read_b128 v[142:145], v213 offset:4096
	ds_read_b128 v[146:149], v214
	ds_read_b128 v[150:153], v214 offset:4096
	ds_read_b128 v[158:161], v215
	ds_read_b128 v[204:207], v215 offset:4096
	s_waitcnt lgkmcnt(0)
	s_cmp_eq_u32 m0, s100
	s_cbranch_scc0 .LSPp_cin
	s_branch .LSPp_qk

; template <int N> __device__ __forceinline__ void wait_bar() { asm volatile("s_waitcnt vmcnt(%0) lgkmcnt(0)\n\ts_barrier" :: "n"(N) : "memory"); }
; #define AT_DMA(tr) do { const unsigned sb_ = (unsigned)__builtin_amdgcn_readfirstlane(dk + (((tr) & (NSTG - 1)) * STAGE)); const size_t ko_ = (size_t)(tr) * 26 * 4096, vo_ = (size_t)(tr) * 640 * 64; \
;         glds16(kg + ko_, sb_ + OFF_K0); if (!WIN) glds16(kg + ko_ + 4096, sb_ + OFF_K1); glds16(vg + vo_, sb_ + OFF_V); if (!WIN) glds16(vg + vo_ + 64 * 64, sb_ + OFF_V + 8192); } while (0)
; template <bool WIN> ...
;     ...
;         if (tr + 2 < NT) wait_bar<2 * NPW>(); else if (tr + 1 < NT) wait_bar<NPW>(); else wait_bar<0>();
;         if (tr + 3 < NT) AT_DMA(tr + 3);
;         const int k0 = (t_lo + tr) * 64;
;         const bool skip = WIN && (k0 > qw + 31 + 128 || k0 + 63 < qw - 128);
;         if (!skip) {
;             const bool near = WIN || ((k0 - (qw + 31)) < 128 && (qw - (k0 + 63)) < 128);
;             const float cinit = near ? 0.f : (k0 > qw ? cfar_hi : cfar_lo);
;             if (__builtin_expect(cinit != cbase, 0)) { cbase = cinit; asm volatile("" ::: "memory");
.LSPs_top:
	s_cmpk_gt_u32 s79, 28
	s_cbranch_scc1 .LSPs_slowtop
	s_waitcnt vmcnt(4) lgkmcnt(0)
	s_barrier
	s_cmp_eq_u32 m0, s100
	s_cbranch_scc0 .LSPs_cin
